# prologue weight transposes rewritten as one batched software-pipelined loop (32 loads in flight, gain applied at store phase)
# speedup vs baseline: 1.0468x; 1.0468x over previous
.LBB0_19:
	s_lshl_b32 s0, s76, 3
	v_mov_b32_e32 v0, v240
	v_writelane_b32 v254, s0, 0
	s_load_dwordx8 s[8:15], s[48:49], 0x0
	v_readfirstlane_b32 s40, v0
	v_writelane_b32 v254, s1, 1
	s_ashr_i32 s39, s40, 6
	s_lshl_b32 s0, s88, 3
	v_writelane_b32 v254, s0, 2
	s_add_i32 s0, s39, s0
	s_add_u32 s1, s78, 0x400000
	v_writelane_b32 v254, s1, 3
	s_addc_u32 s1, s79, 0
	v_writelane_b32 v254, s1, 4
	s_add_u32 s1, s78, 0x1400000
	v_writelane_b32 v254, s1, 5
	s_addc_u32 s1, s79, 0
	v_writelane_b32 v254, s1, 6
	s_add_u32 s1, s78, 0x2400000
	v_writelane_b32 v254, s1, 7
	s_addc_u32 s1, s79, 0
	v_writelane_b32 v254, s1, 8
	s_cmpk_gt_i32 s0, 0x23ff
	v_and_b32_e32 v26, 63, v0
	s_cbranch_scc1 .LBB0_240
	s_waitcnt lgkmcnt(0)
	s_load_dwordx8 s[16:23], s[48:49], 0x58
	s_load_dwordx2 s[6:7], s[48:49], 0x78
	v_readlane_b32 s45, v254, 0
	s_mov_b32 s46, s0
	s_mov_b32 s43, 0
	v_and_b32_e32 v4, 31, v26
	v_lshlrev_b32_e32 v4, 2, v4
	v_lshrrev_b32_e32 v7, 5, v26
	s_lshl_b32 s1, s39, 14
	v_mul_u32_u24_e32 v1, 0x84, v7
	v_add3_u32 v1, v1, v4, s1
	v_and_b32_e32 v8, 7, v26
	v_lshrrev_b32_e32 v9, 3, v26
	v_mul_u32_u24_e32 v2, 0x420, v8
	v_lshl_add_u32 v2, v9, 2, v2
	v_add_u32_e32 v2, s1, v2
	v_lshlrev_b32_e32 v5, 11, v9
	v_lshl_add_u32 v5, v8, 4, v5
	v_lshlrev_b32_e32 v6, 5, v8
	s_waitcnt lgkmcnt(0)
.Ltr_top:
	s_cmpk_gt_i32 s46, 0x23ff
	s_cbranch_scc1 .Ltr_nonew
	s_cmpk_lt_u32 s46, 0x1000
	s_cbranch_scc1 .Ltr_c_ain
	s_cmpk_lt_u32 s46, 0x1400
	s_cbranch_scc1 .Ltr_c_aout
	s_cmpk_lt_u32 s46, 0x1800
	s_cbranch_scc1 .Ltr_c_wkv
	s_cmpk_lt_u32 s46, 0x1c00
	s_cbranch_scc1 .Ltr_c_b0
	s_cmpk_lt_u32 s46, 0x2000
	s_cbranch_scc1 .Ltr_c_b1
	s_add_i32 s3, s46, 0xffffe000
	s_lshr_b32 s4, s3, 9
	s_and_b32 s3, s3, 0x1ff
	s_mov_b32 s41, 10
	s_lshl_b32 s5, s4, 22
	s_add_u32 s24, s6, s5
	s_addc_u32 s25, s7, 0
	s_mov_b64 s[28:29], 0
	s_lshl_b32 s5, s4, 21
	s_add_u32 s30, s78, s5
	s_addc_u32 s31, s79, 0
	s_add_u32 s30, s30, 0x2400000
	s_addc_u32 s31, s31, 0
	s_mov_b32 s42, 0
	s_branch .Ltr_c_done
.Ltr_c_ain:
	s_lshr_b32 s4, s46, 11
	s_and_b32 s3, s46, 0x7ff
	s_mov_b32 s41, 12
	s_lshl_b32 s5, s4, 24
	s_add_u32 s24, s12, s5
	s_addc_u32 s25, s13, 0
	s_mov_b64 s[28:29], s[10:11]
	s_cmp_eq_u64 s[10:11], 0
	s_cbranch_scc1 .Ltr_c_ain_ng
	s_lshl_b32 s5, s4, 12
	s_add_u32 s28, s10, s5
	s_addc_u32 s29, s11, 0
.Ltr_c_ain_ng:
	s_lshl_b32 s5, s4, 23
	s_add_u32 s30, s78, s5
	s_addc_u32 s31, s79, 0
	s_add_u32 s30, s30, 0x400000
	s_addc_u32 s31, s31, 0
	s_mov_b32 s42, 1
	s_branch .Ltr_c_done
.Ltr_c_aout:
	s_add_i32 s3, s46, 0xfffff000
	s_lshr_b32 s4, s3, 9
	s_and_b32 s3, s3, 0x1ff
	s_mov_b32 s41, 10
	s_lshl_b32 s5, s4, 22
	s_add_u32 s24, s14, s5
	s_addc_u32 s25, s15, 0
	s_mov_b64 s[28:29], 0
	s_lshl_b32 s5, s4, 21
	s_add_u32 s30, s78, s5
	s_addc_u32 s31, s79, 0
	s_add_u32 s30, s30, 0x1400000
	s_addc_u32 s31, s31, 0
	s_mov_b32 s42, 0
	s_branch .Ltr_c_done
.Ltr_c_wkv:
	s_add_i32 s3, s46, 0xffffec00
	s_mov_b32 s41, 11
	s_mov_b64 s[24:25], s[18:19]
	s_mov_b64 s[28:29], s[16:17]
	s_add_u32 s30, s78, 0x1800000
	s_addc_u32 s31, s79, 0
	s_mov_b32 s42, 1
	s_branch .Ltr_c_done
.Ltr_c_b0:
	s_add_i32 s3, s46, 0xffffe800
	s_mov_b32 s41, 11
	s_mov_b64 s[24:25], s[22:23]
	s_mov_b64 s[28:29], s[20:21]
	s_add_u32 s30, s78, 0x1c00000
	s_addc_u32 s31, s79, 0
	s_mov_b32 s42, 1
	s_branch .Ltr_c_done
.Ltr_c_b1:
	s_add_i32 s3, s46, 0xffffe400
	s_mov_b32 s41, 11
	s_add_u32 s24, s22, 0x800000
	s_addc_u32 s25, s23, 0
	s_mov_b64 s[28:29], s[20:21]
	s_cmp_eq_u64 s[20:21], 0
	s_cbranch_scc1 .Ltr_c_b1_ng
	s_add_u32 s28, s20, 0x1000
	s_addc_u32 s29, s21, 0
.Ltr_c_b1_ng:
	s_add_u32 s30, s78, 0x2000000
	s_addc_u32 s31, s79, 0
	s_mov_b32 s42, 1
.Ltr_c_done:
	s_sub_u32 s4, s41, 5
	s_lshr_b32 s5, s3, s4
	s_lshl_b32 s34, 1, s4
	s_sub_u32 s34, s34, 1
	s_and_b32 s3, s3, s34
	s_add_u32 s4, s41, 8
	s_lshl_b32 s4, s5, s4
	s_lshl_b32 s34, s3, 7
	s_add_u32 s4, s4, s34
	s_add_u32 s24, s24, s4
	s_addc_u32 s25, s25, 0
	s_add_u32 s4, s41, 2
	s_lshl_b32 s26, 1, s4
	s_lshl_b32 s27, s26, 1
	s_lshl_b32 s4, s3, 5
	s_cmp_eq_u32 s42, 0
	s_cbranch_scc1 .Ltr_noperm
	s_lshr_b32 s4, s3, 3
	s_lshl_b32 s4, s4, 8
	s_and_b32 s34, s3, 1
	s_lshl_b32 s34, s34, 2
	s_bfe_u32 s35, s3, 0x20001
	s_or_b32 s34, s34, s35
	s_lshl_b32 s34, s34, 5
	s_or_b32 s4, s4, s34
.Ltr_noperm:
	s_lshl_b32 s4, s4, 11
	s_lshl_b32 s34, s5, 7
	s_add_u32 s4, s4, s34
	s_add_u32 s30, s30, s4
	s_addc_u32 s31, s31, 0
	s_cmp_eq_u64 s[28:29], 0
	s_cbranch_scc1 .Ltr_g1
	s_lshl_b32 s4, s5, 8
	s_add_u32 s28, s28, s4
	s_addc_u32 s29, s29, 0
	global_load_dwordx4 v[10:13], v6, s[28:29]
	global_load_dwordx4 v[14:17], v6, s[28:29] offset:16
	s_branch .Ltr_g2
.Ltr_g1:
	v_mov_b32_e32 v10, 1.0
	v_mov_b32_e32 v11, 1.0
	v_mov_b32_e32 v12, 1.0
	v_mov_b32_e32 v13, 1.0
	v_mov_b32_e32 v14, 1.0
	v_mov_b32_e32 v15, 1.0
	v_mov_b32_e32 v16, 1.0
	v_mov_b32_e32 v17, 1.0
.Ltr_g2:
	v_mad_u32_u24 v3, v7, s26, v4
	global_load_dword v32, v3, s[24:25] nt
	s_add_u32 s24, s24, s27
	s_addc_u32 s25, s25, 0
	global_load_dword v33, v3, s[24:25] nt
	s_add_u32 s24, s24, s27
	s_addc_u32 s25, s25, 0
	global_load_dword v34, v3, s[24:25] nt
	s_add_u32 s24, s24, s27
	s_addc_u32 s25, s25, 0
	global_load_dword v35, v3, s[24:25] nt
	s_add_u32 s24, s24, s27
	s_addc_u32 s25, s25, 0
	global_load_dword v36, v3, s[24:25] nt
	s_add_u32 s24, s24, s27
	s_addc_u32 s25, s25, 0
	global_load_dword v37, v3, s[24:25] nt
	s_add_u32 s24, s24, s27
	s_addc_u32 s25, s25, 0
	global_load_dword v38, v3, s[24:25] nt
	s_add_u32 s24, s24, s27
	s_addc_u32 s25, s25, 0
	global_load_dword v39, v3, s[24:25] nt
	s_add_u32 s24, s24, s27
	s_addc_u32 s25, s25, 0
	global_load_dword v40, v3, s[24:25] nt
	s_add_u32 s24, s24, s27
	s_addc_u32 s25, s25, 0
	global_load_dword v41, v3, s[24:25] nt
	s_add_u32 s24, s24, s27
	s_addc_u32 s25, s25, 0
	global_load_dword v42, v3, s[24:25] nt
	s_add_u32 s24, s24, s27
	s_addc_u32 s25, s25, 0
	global_load_dword v43, v3, s[24:25] nt
	s_add_u32 s24, s24, s27
	s_addc_u32 s25, s25, 0
	global_load_dword v44, v3, s[24:25] nt
	s_add_u32 s24, s24, s27
	s_addc_u32 s25, s25, 0
	global_load_dword v45, v3, s[24:25] nt
	s_add_u32 s24, s24, s27
	s_addc_u32 s25, s25, 0
	global_load_dword v46, v3, s[24:25] nt
	s_add_u32 s24, s24, s27
	s_addc_u32 s25, s25, 0
	global_load_dword v47, v3, s[24:25] nt
	s_add_u32 s24, s24, s27
	s_addc_u32 s25, s25, 0
	global_load_dword v48, v3, s[24:25] nt
	s_add_u32 s24, s24, s27
	s_addc_u32 s25, s25, 0
	global_load_dword v49, v3, s[24:25] nt
	s_add_u32 s24, s24, s27
	s_addc_u32 s25, s25, 0
	global_load_dword v50, v3, s[24:25] nt
	s_add_u32 s24, s24, s27
	s_addc_u32 s25, s25, 0
	global_load_dword v51, v3, s[24:25] nt
	s_add_u32 s24, s24, s27
	s_addc_u32 s25, s25, 0
	global_load_dword v52, v3, s[24:25] nt
	s_add_u32 s24, s24, s27
	s_addc_u32 s25, s25, 0
	global_load_dword v53, v3, s[24:25] nt
	s_add_u32 s24, s24, s27
	s_addc_u32 s25, s25, 0
	global_load_dword v54, v3, s[24:25] nt
	s_add_u32 s24, s24, s27
	s_addc_u32 s25, s25, 0
	global_load_dword v55, v3, s[24:25] nt
	s_add_u32 s24, s24, s27
	s_addc_u32 s25, s25, 0
	global_load_dword v56, v3, s[24:25] nt
	s_add_u32 s24, s24, s27
	s_addc_u32 s25, s25, 0
	global_load_dword v57, v3, s[24:25] nt
	s_add_u32 s24, s24, s27
	s_addc_u32 s25, s25, 0
	global_load_dword v58, v3, s[24:25] nt
	s_add_u32 s24, s24, s27
	s_addc_u32 s25, s25, 0
	global_load_dword v59, v3, s[24:25] nt
	s_add_u32 s24, s24, s27
	s_addc_u32 s25, s25, 0
	global_load_dword v60, v3, s[24:25] nt
	s_add_u32 s24, s24, s27
	s_addc_u32 s25, s25, 0
	global_load_dword v61, v3, s[24:25] nt
	s_add_u32 s24, s24, s27
	s_addc_u32 s25, s25, 0
	global_load_dword v62, v3, s[24:25] nt
	s_add_u32 s24, s24, s27
	s_addc_u32 s25, s25, 0
	global_load_dword v63, v3, s[24:25] nt
	s_mov_b32 s44, 1
	s_branch .Ltr_st
.Ltr_nonew:
	s_mov_b32 s44, 0
.Ltr_st:
	s_cmp_eq_u32 s43, 0
	s_cbranch_scc1 .Ltr_w0
	ds_read2_b32 v[64:65], v2 offset0:0 offset1:33
	ds_read2_b32 v[66:67], v2 offset0:66 offset1:99
	ds_read2_b32 v[68:69], v2 offset0:132 offset1:165
	ds_read2_b32 v[70:71], v2 offset0:198 offset1:231
	ds_read2_b32 v[72:73], v2 offset0:8 offset1:41
	ds_read2_b32 v[74:75], v2 offset0:74 offset1:107
	ds_read2_b32 v[76:77], v2 offset0:140 offset1:173
	ds_read2_b32 v[78:79], v2 offset0:206 offset1:239
	ds_read2_b32 v[80:81], v2 offset0:16 offset1:49
	ds_read2_b32 v[82:83], v2 offset0:82 offset1:115
	ds_read2_b32 v[84:85], v2 offset0:148 offset1:181
	ds_read2_b32 v[86:87], v2 offset0:214 offset1:247
	ds_read2_b32 v[88:89], v2 offset0:24 offset1:57
	ds_read2_b32 v[90:91], v2 offset0:90 offset1:123
	ds_read2_b32 v[92:93], v2 offset0:156 offset1:189
	ds_read2_b32 v[94:95], v2 offset0:222 offset1:255
	s_waitcnt lgkmcnt(0)
	v_mul_f32_e32 v64, v64, v18
	v_mul_f32_e32 v65, v65, v19
	v_cvt_pk_bf16_f32 v96, v64, v65
	v_mul_f32_e32 v66, v66, v20
	v_mul_f32_e32 v67, v67, v21
	v_cvt_pk_bf16_f32 v97, v66, v67
	v_mul_f32_e32 v68, v68, v22
	v_mul_f32_e32 v69, v69, v23
	v_cvt_pk_bf16_f32 v98, v68, v69
	v_mul_f32_e32 v70, v70, v24
	v_mul_f32_e32 v71, v71, v25
	v_cvt_pk_bf16_f32 v99, v70, v71
	v_mul_f32_e32 v72, v72, v18
	v_mul_f32_e32 v73, v73, v19
	v_cvt_pk_bf16_f32 v100, v72, v73
	v_mul_f32_e32 v74, v74, v20
	v_mul_f32_e32 v75, v75, v21
	v_cvt_pk_bf16_f32 v101, v74, v75
	v_mul_f32_e32 v76, v76, v22
	v_mul_f32_e32 v77, v77, v23
	v_cvt_pk_bf16_f32 v102, v76, v77
	v_mul_f32_e32 v78, v78, v24
	v_mul_f32_e32 v79, v79, v25
	v_cvt_pk_bf16_f32 v103, v78, v79
	v_mul_f32_e32 v80, v80, v18
	v_mul_f32_e32 v81, v81, v19
	v_cvt_pk_bf16_f32 v104, v80, v81
	v_mul_f32_e32 v82, v82, v20
	v_mul_f32_e32 v83, v83, v21
	v_cvt_pk_bf16_f32 v105, v82, v83
	v_mul_f32_e32 v84, v84, v22
	v_mul_f32_e32 v85, v85, v23
	v_cvt_pk_bf16_f32 v106, v84, v85
	v_mul_f32_e32 v86, v86, v24
	v_mul_f32_e32 v87, v87, v25
	v_cvt_pk_bf16_f32 v107, v86, v87
	v_mul_f32_e32 v88, v88, v18
	v_mul_f32_e32 v89, v89, v19
	v_cvt_pk_bf16_f32 v108, v88, v89
	v_mul_f32_e32 v90, v90, v20
	v_mul_f32_e32 v91, v91, v21
	v_cvt_pk_bf16_f32 v109, v90, v91
	v_mul_f32_e32 v92, v92, v22
	v_mul_f32_e32 v93, v93, v23
	v_cvt_pk_bf16_f32 v110, v92, v93
	v_mul_f32_e32 v94, v94, v24
	v_mul_f32_e32 v95, v95, v25
	v_cvt_pk_bf16_f32 v111, v94, v95
	global_store_dwordx4 v5, v[96:99], s[36:37] sc1
	s_add_u32 s36, s36, 0x4000
	s_addc_u32 s37, s37, 0
	global_store_dwordx4 v5, v[100:103], s[36:37] sc1
	s_add_u32 s36, s36, 0x4000
	s_addc_u32 s37, s37, 0
	global_store_dwordx4 v5, v[104:107], s[36:37] sc1
	s_add_u32 s36, s36, 0x4000
	s_addc_u32 s37, s37, 0
	global_store_dwordx4 v5, v[108:111], s[36:37] sc1
	s_cmp_eq_u32 s44, 0
	s_cbranch_scc1 .Ltr_done
	s_waitcnt vmcnt(4)
	s_branch .Ltr_w1
.Ltr_w0:
	s_cmp_eq_u32 s44, 0
	s_cbranch_scc1 .Ltr_done
	s_waitcnt vmcnt(0)
.Ltr_w1:
	v_mov_b32_e32 v18, v10
	v_mov_b32_e32 v19, v11
	v_mov_b32_e32 v20, v12
	v_mov_b32_e32 v21, v13
	v_mov_b32_e32 v22, v14
	v_mov_b32_e32 v23, v15
	v_mov_b32_e32 v24, v16
	v_mov_b32_e32 v25, v17
	s_mov_b64 s[36:37], s[30:31]
	ds_write_b32 v1, v32
	ds_write_b32 v1, v33 offset:264
	ds_write_b32 v1, v34 offset:528
	ds_write_b32 v1, v35 offset:792
	ds_write_b32 v1, v36 offset:1056
	ds_write_b32 v1, v37 offset:1320
	ds_write_b32 v1, v38 offset:1584
	ds_write_b32 v1, v39 offset:1848
	ds_write_b32 v1, v40 offset:2112
	ds_write_b32 v1, v41 offset:2376
	ds_write_b32 v1, v42 offset:2640
	ds_write_b32 v1, v43 offset:2904
	ds_write_b32 v1, v44 offset:3168
	ds_write_b32 v1, v45 offset:3432
	ds_write_b32 v1, v46 offset:3696
	ds_write_b32 v1, v47 offset:3960
	ds_write_b32 v1, v48 offset:4224
	ds_write_b32 v1, v49 offset:4488
	ds_write_b32 v1, v50 offset:4752
	ds_write_b32 v1, v51 offset:5016
	ds_write_b32 v1, v52 offset:5280
	ds_write_b32 v1, v53 offset:5544
	ds_write_b32 v1, v54 offset:5808
	ds_write_b32 v1, v55 offset:6072
	ds_write_b32 v1, v56 offset:6336
	ds_write_b32 v1, v57 offset:6600
	ds_write_b32 v1, v58 offset:6864
	ds_write_b32 v1, v59 offset:7128
	ds_write_b32 v1, v60 offset:7392
	ds_write_b32 v1, v61 offset:7656
	ds_write_b32 v1, v62 offset:7920
	ds_write_b32 v1, v63 offset:8184
	s_waitcnt lgkmcnt(0)
	s_mov_b32 s43, 1
	s_add_i32 s46, s46, s45
	s_branch .Ltr_top
.Ltr_done:
.LBB0_240:
	s_cmpk_lt_i32 s0, 0x4000
	v_mov_b32_e32 v9, 0
	v_mbcnt_lo_u32_b32 v10, -1, 0
	v_lshlrev_b32_e32 v2, 2, v26
	s_cbranch_scc0 .LBB0_245
	v_mbcnt_hi_u32_b32 v3, -1, v10
	v_and_b32_e32 v1, 64, v3
	v_add_u32_e32 v4, 64, v1
	v_xor_b32_e32 v1, 1, v3
	v_cmp_lt_i32_e32 vcc, v1, v4
	v_xor_b32_e32 v5, 2, v3
	s_ashr_i32 s1, s0, 31
	v_cndmask_b32_e32 v1, v3, v1, vcc
	v_cmp_lt_i32_e32 vcc, v5, v4
	s_waitcnt lgkmcnt(0)
	s_lshl_b64 s[10:11], s[0:1], 7
	s_lshl_b64 s[12:13], s[0:1], 6
	v_cndmask_b32_e32 v5, v3, v5, vcc
	v_lshlrev_b32_e32 v11, 2, v5
	v_xor_b32_e32 v5, 4, v3
	v_cmp_lt_i32_e32 vcc, v5, v4
	s_lshl_b64 s[14:15], s[0:1], 12
	v_cmp_gt_u32_e64 s[4:5], 16, v26
	v_cndmask_b32_e32 v5, v3, v5, vcc
	v_lshlrev_b32_e32 v12, 2, v5
	v_xor_b32_e32 v5, 8, v3
	v_cmp_lt_i32_e32 vcc, v5, v4
	v_cmp_eq_u32_e64 s[6:7], 0, v26
	v_lshlrev_b32_e32 v1, 2, v1
	v_cndmask_b32_e32 v5, v3, v5, vcc
	v_lshlrev_b32_e32 v13, 2, v5
	v_xor_b32_e32 v5, 16, v3
	v_cmp_lt_i32_e32 vcc, v5, v4
	s_mov_b32 s1, 0xa800000
	s_mov_b32 s3, 0xb000000
	v_cndmask_b32_e32 v5, v3, v5, vcc
	v_lshlrev_b32_e32 v14, 2, v5
	v_xor_b32_e32 v5, 32, v3
	v_cmp_lt_i32_e32 vcc, v5, v4
	s_nop 1
	v_cndmask_b32_e32 v3, v3, v5, vcc
	v_lshlrev_b32_e32 v15, 2, v3
	v_lshlrev_b32_e32 v3, 17, v26
	v_and_b32_e32 v8, 0x600000, v3
	v_lshl_add_u64 v[4:5], v[8:9], 0, s[10:11]
	v_and_b32_e32 v3, 15, v0
	v_lshl_or_b32 v4, v3, 3, v4
	v_readlane_b32 s10, v254, 0
	v_mov_b32_e32 v3, v9
	v_readlane_b32 s11, v254, 1
	s_mov_b32 s16, s10
	s_ashr_i32 s17, s10, 31
	v_lshl_add_u64 v[6:7], s[12:13], 0, v[2:3]
	s_mov_b64 s[12:13], 0x100000
	s_lshl_b64 s[10:11], s[16:17], 7
	v_lshl_add_u64 v[6:7], v[6:7], 0, s[12:13]
	s_lshl_b64 s[12:13], s[16:17], 6
	s_add_u32 s8, s8, s14
	v_lshlrev_b32_e32 v8, 4, v26
	s_addc_u32 s9, s9, s15
	v_lshl_add_u64 v[8:9], s[8:9], 0, v[8:9]
	s_mov_b64 s[8:9], 0xc00
	v_lshl_add_u64 v[8:9], v[8:9], 0, s[8:9]
	s_mov_b32 s8, s16
	v_writelane_b32 v254, s8, 0
	s_nop 1
	v_writelane_b32 v254, s9, 1
	s_lshl_b64 s[8:9], s[16:17], 12
	s_branch .LBB0_243
